# final_norm loop: next row's loads prefetched into a second register set, counted vmcnt(8) leaves the previous row's stores in flight
# speedup vs baseline: 1.0097x; 1.0026x over previous
; __device__ __forceinline__ void final_norm(KA a, int gw, int NGW, int lane) {
;     const float* ssqp = (const float*)(a.ws + WS_SSQ) + 4 * SSQ_STAGE; const float* gf = a.in[I_NFIN]; const bf16_t* HBp = (const bf16_t*)(a.ws + WS_HB);
;     f32x4 g[8];
; #pragma unroll
;     for (int i = 0; i < 4; ++i) { g[2 * i] = *(const f32x4*)(gf + i * 512 + lane * 8); g[2 * i + 1] = *(const f32x4*)(gf + i * 512 + lane * 8 + 4); }
;     for (int row = gw; row < M_; row += NGW) {
;         float t = ssqp[(size_t)row * 32 + (lane & 31)];
;         u32x4 v[4];
; #pragma unroll
;         for (int i = 0; i < 4; ++i) v[i] = *(const u32x4*)(HBp + (size_t)row * 2048 + i * 512 + lane * 8);
.LBB0_1428:
	s_or_b64 exec, exec, s[36:37]
	v_readlane_b32 s1, v250, 4
	s_waitcnt lgkmcnt(0)
	s_barrier
	s_lshl_b32 s0, s2, 3
	s_add_i32 s2, s0, s1
	s_cmpk_gt_i32 s2, 0x3fff
	s_cbranch_scc1 .LBB0_1431
	s_load_dwordx2 s[0:1], s[62:63], 0x18
	s_load_dwordx4 s[4:7], s[62:63], 0x88
	v_lshlrev_b32_e32 v36, 3, v167
	v_ashrrev_i32_e32 v37, 31, v36
	v_lshlrev_b64 v[32:33], 2, v[36:37]
	s_waitcnt lgkmcnt(0)
	v_lshl_add_u64 v[34:35], s[0:1], 0, v[32:33]
	s_mov_b64 s[0:1], 0x1800
	v_lshl_add_u64 v[38:39], v[34:35], 0, s[0:1]
	v_add_co_u32_e32 v40, vcc, 0x1000, v34
	s_mov_b64 s[0:1], 0x1000
	s_nop 0
	v_addc_co_u32_e32 v41, vcc, 0, v35, vcc
	v_lshl_add_u64 v[42:43], v[34:35], 0, s[0:1]
	global_load_dwordx4 v[0:3], v[38:39], off offset:16
	global_load_dwordx4 v[4:7], v[40:41], off
	global_load_dwordx4 v[8:11], v[40:41], off offset:2048
	global_load_dwordx4 v[12:15], v[42:43], off offset:16
	global_load_dwordx4 v[16:19], v[34:35], off offset:2064
	global_load_dwordx4 v[20:23], v[34:35], off offset:2048
	global_load_dwordx4 v[24:27], v[34:35], off offset:16
	global_load_dwordx4 v[28:31], v[34:35], off
	s_ashr_i32 s3, s2, 31
	s_lshl_b64 s[0:1], s[2:3], 13
	s_add_u32 s0, s4, s0
	v_and_b32_e32 v34, 31, v167
	v_lshlrev_b32_e32 v35, 2, v167
	s_addc_u32 s1, s5, s1
	s_lshl_b64 s[4:5], s[2:3], 7
	v_xor_b32_e32 v38, 4, v35
	v_xor_b32_e32 v39, 8, v35
	v_xor_b32_e32 v40, 16, v35
	v_xor_b32_e32 v41, 32, v35
	v_xor_b32_e32 v42, 64, v35
	v_lshl_add_u64 v[32:33], s[0:1], 0, v[32:33]
	s_mov_b64 s[0:1], 0x1810
	s_ashr_i32 s39, s38, 31
	v_lshl_or_b32 v34, v34, 2, s4
	v_mov_b32_e32 v35, s5
	s_mov_b64 s[4:5], 0x23000000
	s_lshl_b64 s[8:9], s[2:3], 12
	v_lshl_add_u64 v[32:33], v[32:33], 0, s[0:1]
	s_lshl_b64 s[0:1], s[38:39], 13
	v_lshl_add_u64 v[34:35], v[34:35], 0, s[4:5]
	s_lshl_b64 s[4:5], s[38:39], 7
	v_lshl_add_u64 v[36:37], v[36:37], 1, s[8:9]
	s_lshl_b64 s[8:9], s[38:39], 12
	v_mov_b32_e32 v43, 0x358637bd
	s_mov_b32 s3, 0x800000
	s_movk_i32 s10, 0xf000
	v_lshl_add_u64 v[118:119], s[6:7], 0, v[34:35]
	global_load_dword v116, v[118:119], off
	v_lshl_add_u64 v[118:119], s[6:7], 0, v[36:37]
	s_nop 0
	v_add_co_u32_e32 v118, vcc, 0xc800000, v118
	s_nop 1
	v_addc_co_u32_e32 v119, vcc, 0, v119, vcc
	global_load_dwordx4 v[100:103], v[118:119], off
	global_load_dwordx4 v[104:107], v[118:119], off offset:1024
	global_load_dwordx4 v[108:111], v[118:119], off offset:2048
	global_load_dwordx4 v[112:115], v[118:119], off offset:3072
	v_lshl_add_u64 v[34:35], v[34:35], 0, s[4:5]
	v_lshl_add_u64 v[36:37], v[36:37], 0, s[8:9]
	s_waitcnt vmcnt(0)
.LBB0_1430:
	s_waitcnt vmcnt(8)
	v_mov_b32_e32 v78, v116
	v_mov_b32_e32 v44, v100
	v_mov_b32_e32 v45, v101
	v_mov_b32_e32 v46, v102
	v_mov_b32_e32 v47, v103
	v_mov_b32_e32 v48, v104
	v_mov_b32_e32 v49, v105
	v_mov_b32_e32 v50, v106
	v_mov_b32_e32 v51, v107
	v_mov_b32_e32 v52, v108
	v_mov_b32_e32 v53, v109
	v_mov_b32_e32 v54, v110
	v_mov_b32_e32 v55, v111
	v_mov_b32_e32 v56, v112
	v_mov_b32_e32 v57, v113
	v_mov_b32_e32 v58, v114
	v_mov_b32_e32 v59, v115
	v_add_co_u32_e32 v76, vcc, s10, v32
	s_nop 1
	v_addc_co_u32_e32 v77, vcc, -1, v33, vcc
	s_add_i32 s2, s2, s38
	s_cmpk_lt_i32 s2, 0x4000
	s_cbranch_scc0 .Lfn_nopf
	v_lshl_add_u64 v[118:119], s[6:7], 0, v[34:35]
	global_load_dword v116, v[118:119], off
	v_lshl_add_u64 v[118:119], s[6:7], 0, v[36:37]
	s_nop 0
	v_add_co_u32_e32 v118, vcc, 0xc800000, v118
	s_nop 1
	v_addc_co_u32_e32 v119, vcc, 0, v119, vcc
	global_load_dwordx4 v[100:103], v[118:119], off
	global_load_dwordx4 v[104:107], v[118:119], off offset:1024
	global_load_dwordx4 v[108:111], v[118:119], off offset:2048
	global_load_dwordx4 v[112:115], v[118:119], off offset:3072
	v_lshl_add_u64 v[34:35], v[34:35], 0, s[4:5]
	v_lshl_add_u64 v[36:37], v[36:37], 0, s[8:9]
; __device__ __forceinline__ float shx(float v, int mask, int lane) { return __int_as_float(__builtin_amdgcn_ds_bpermute((lane ^ mask) << 2, __float_as_int(v))); }
; __device__ __forceinline__ float bf_lo(unsigned w) { return __uint_as_float(w << 16); }
; __device__ __forceinline__ float bf_hi(unsigned w) { return __uint_as_float(w & 0xffff0000u); }
; __device__ __forceinline__ void final_norm(KA a, int gw, int NGW, int lane) {
;     ...
;         for (int o = 1; o < 32; o <<= 1) t += shx(t, o, lane);
;         const float r = rsqrtf(t * (1.0f / 2048.0f) + RMS_EPS);
; #pragma unroll
;         for (int i = 0; i < 4; ++i) { float* o = a.out + (size_t)row * 2048 + i * 512 + lane * 8; const f32x4 g0 = g[2 * i], g1 = g[2 * i + 1];
;             *(f32x4*)o = (f32x4){bf_lo(v[i].x) * r * g0[0], bf_hi(v[i].x) * r * g0[1], bf_lo(v[i].y) * r * g0[2], bf_hi(v[i].y) * r * g0[3]};
;             *(f32x4*)(o + 4) = (f32x4){bf_lo(v[i].z) * r * g1[0], bf_hi(v[i].z) * r * g1[1], bf_lo(v[i].w) * r * g1[2], bf_hi(v[i].w) * r * g1[3]}; }
.Lfn_nopf:
	ds_bpermute_b32 v79, v38, v78
	s_waitcnt lgkmcnt(0)
	v_add_f32_e32 v78, v78, v79
	ds_bpermute_b32 v79, v39, v78
	v_lshlrev_b32_e32 v60, 16, v44
	v_and_b32_e32 v61, 0xffff0000, v44
	v_lshlrev_b32_e32 v44, 16, v45
	s_waitcnt lgkmcnt(0)
	v_add_f32_e32 v78, v78, v79
	ds_bpermute_b32 v79, v40, v78
	v_and_b32_e32 v45, 0xffff0000, v45
	v_lshlrev_b32_e32 v62, 16, v46
	v_and_b32_e32 v63, 0xffff0000, v46
	v_lshlrev_b32_e32 v46, 16, v47
	s_waitcnt lgkmcnt(0)
	v_add_f32_e32 v78, v78, v79
	ds_bpermute_b32 v79, v41, v78
	v_and_b32_e32 v47, 0xffff0000, v47
	v_lshlrev_b32_e32 v64, 16, v48
	v_and_b32_e32 v65, 0xffff0000, v48
	v_lshlrev_b32_e32 v48, 16, v49
	s_waitcnt lgkmcnt(0)
	v_add_f32_e32 v78, v78, v79
	ds_bpermute_b32 v79, v42, v78
	v_and_b32_e32 v49, 0xffff0000, v49
	v_lshlrev_b32_e32 v66, 16, v50
	v_and_b32_e32 v67, 0xffff0000, v50
	v_lshlrev_b32_e32 v50, 16, v51
	s_waitcnt lgkmcnt(0)
	v_add_f32_e32 v78, v78, v79
	v_fmamk_f32 v78, v78, 0x3a000000, v43
	v_mul_f32_e32 v79, 0x4b800000, v78
	v_cmp_gt_f32_e32 vcc, s3, v78
	v_and_b32_e32 v51, 0xffff0000, v51
	v_lshlrev_b32_e32 v68, 16, v52
	v_cndmask_b32_e32 v78, v78, v79, vcc
	v_rsq_f32_e32 v78, v78
	v_and_b32_e32 v69, 0xffff0000, v52
	v_lshlrev_b32_e32 v52, 16, v53
	v_and_b32_e32 v53, 0xffff0000, v53
	v_mul_f32_e32 v79, 0x45800000, v78
	v_cndmask_b32_e32 v78, v78, v79, vcc
	v_lshlrev_b32_e32 v70, 16, v54
	v_and_b32_e32 v71, 0xffff0000, v54
	v_lshlrev_b32_e32 v54, 16, v55
	v_and_b32_e32 v55, 0xffff0000, v55
	v_lshlrev_b32_e32 v72, 16, v56
	v_and_b32_e32 v73, 0xffff0000, v56
	v_lshlrev_b32_e32 v56, 16, v57
	v_and_b32_e32 v57, 0xffff0000, v57
	v_lshlrev_b32_e32 v74, 16, v58
	v_and_b32_e32 v75, 0xffff0000, v58
	v_lshlrev_b32_e32 v58, 16, v59
	v_and_b32_e32 v59, 0xffff0000, v59
	v_pk_mul_f32 v[60:61], v[78:79], v[60:61] op_sel_hi:[0,1]
	v_pk_mul_f32 v[80:81], v[78:79], v[44:45] op_sel_hi:[0,1]
	v_pk_mul_f32 v[62:63], v[78:79], v[62:63] op_sel_hi:[0,1]
	v_pk_mul_f32 v[82:83], v[78:79], v[46:47] op_sel_hi:[0,1]
	v_pk_mul_f32 v[64:65], v[78:79], v[64:65] op_sel_hi:[0,1]
	v_pk_mul_f32 v[84:85], v[78:79], v[48:49] op_sel_hi:[0,1]
	v_pk_mul_f32 v[66:67], v[78:79], v[66:67] op_sel_hi:[0,1]
	v_pk_mul_f32 v[86:87], v[78:79], v[50:51] op_sel_hi:[0,1]
	v_pk_mul_f32 v[68:69], v[78:79], v[68:69] op_sel_hi:[0,1]
	v_pk_mul_f32 v[88:89], v[78:79], v[52:53] op_sel_hi:[0,1]
	v_pk_mul_f32 v[70:71], v[78:79], v[70:71] op_sel_hi:[0,1]
	v_pk_mul_f32 v[90:91], v[78:79], v[54:55] op_sel_hi:[0,1]
	v_pk_mul_f32 v[72:73], v[78:79], v[72:73] op_sel_hi:[0,1]
	v_pk_mul_f32 v[92:93], v[78:79], v[56:57] op_sel_hi:[0,1]
	v_pk_mul_f32 v[74:75], v[78:79], v[74:75] op_sel_hi:[0,1]
	v_pk_mul_f32 v[78:79], v[78:79], v[58:59] op_sel_hi:[0,1]
	v_pk_mul_f32 v[44:45], v[28:29], v[60:61]
	v_pk_mul_f32 v[46:47], v[30:31], v[80:81]
	v_pk_mul_f32 v[48:49], v[24:25], v[62:63]
	v_pk_mul_f32 v[50:51], v[26:27], v[82:83]
	v_pk_mul_f32 v[52:53], v[20:21], v[64:65]
	v_pk_mul_f32 v[54:55], v[22:23], v[84:85]
	v_pk_mul_f32 v[56:57], v[16:17], v[66:67]
	v_pk_mul_f32 v[58:59], v[18:19], v[86:87]
	v_pk_mul_f32 v[60:61], v[4:5], v[68:69]
	v_pk_mul_f32 v[62:63], v[6:7], v[88:89]
	v_pk_mul_f32 v[64:65], v[12:13], v[70:71]
	v_pk_mul_f32 v[66:67], v[14:15], v[90:91]
	v_pk_mul_f32 v[68:69], v[8:9], v[72:73]
	v_pk_mul_f32 v[70:71], v[10:11], v[92:93]
	v_pk_mul_f32 v[72:73], v[0:1], v[74:75]
	v_pk_mul_f32 v[74:75], v[2:3], v[78:79]
	global_store_dwordx4 v[76:77], v[44:47], off offset:-2064
	global_store_dwordx4 v[76:77], v[48:51], off offset:-2048
	global_store_dwordx4 v[76:77], v[52:55], off offset:-16
	global_store_dwordx4 v[32:33], v[56:59], off offset:-4096
	global_store_dwordx4 v[32:33], v[60:63], off offset:-2064
	global_store_dwordx4 v[32:33], v[64:67], off offset:-2048
	global_store_dwordx4 v[32:33], v[68:71], off offset:-16
	global_store_dwordx4 v[32:33], v[72:75], off
	v_lshl_add_u64 v[32:33], v[32:33], 0, s[0:1]
	s_cbranch_scc1 .LBB0_1430
